# top-k rank count loop stops at the last causal block (future blocks can never change a causal rank)
# speedup vs baseline: 1.0049x; 1.0048x over previous
; #define LDS_FENCE() asm volatile("s_waitcnt lgkmcnt(0)" ::: "memory")
; DI void nsa_wg_unit(const Args& a, int l, int b, int g, int tb, unsigned char* lds, int tid_in, bool stage) {
;     ...
;       LDS_FENCE();
; #pragma unroll
;       for (int c = 0; c < CPL; ++c) IA[tok * 65 + qtr * CPL + c] = mv[c];
;       LDS_FENCE();
;       int cnt[CPL];
; #pragma unroll
;       for (int c = 0; c < CPL; ++c) cnt[c] = (qtr * CPL + c <= jt) ? 0 : 64;
;       if (jt >= 16)
; #pragma unroll 4
;       for (int i = 0; i < 64; ++i) { const float vi = IA[tok * 65 + i];
; #pragma unroll
;           for (int c = 0; c < CPL; ++c) { const int j = qtr * CPL + c; cnt[c] += ((vi > mv[c]) || (vi == mv[c] && i < j)) ? 1 : 0; } }
.LBB0_154:
	s_or_b64 exec, exec, s[0:1]
	v_cmp_lt_u32_e32 vcc, s33, v0
	v_mul_u32_u24_e32 v30, 0x104, v1
	v_lshlrev_b32_e32 v1, 5, v32
	v_cndmask_b32_e64 v34, 0, 64, vcc
	v_cmp_gt_u32_e32 vcc, s33, v0
	v_add3_u32 v1, s9, v30, v1
	s_waitcnt lgkmcnt(0)
	ds_write2_b32 v1, v4, v2 offset1:1
	ds_write2_b32 v1, v10, v8 offset0:2 offset1:3
	ds_write2_b32 v1, v18, v16 offset0:4 offset1:5
	ds_write2_b32 v1, v26, v24 offset0:6 offset1:7
	v_cndmask_b32_e64 v37, 64, 0, vcc
	v_cmp_lt_u32_e32 vcc, s33, v6
	s_waitcnt lgkmcnt(0)
	s_cmp_lt_u32 s33, 16
	s_nop 0
	v_cndmask_b32_e64 v40, 0, 64, vcc
	v_cmp_lt_u32_e32 vcc, s33, v12
	s_nop 1
	v_cndmask_b32_e64 v45, 0, 64, vcc
	v_cmp_lt_u32_e32 vcc, s33, v14
	s_nop 1
	v_cndmask_b32_e64 v46, 0, 64, vcc
	v_cmp_lt_u32_e32 vcc, s33, v20
	s_nop 1
	v_cndmask_b32_e64 v42, 0, 64, vcc
	v_cmp_lt_u32_e32 vcc, s33, v22
	s_nop 1
	v_cndmask_b32_e64 v38, 0, 64, vcc
	v_cmp_lt_u32_e32 vcc, s33, v28
	s_nop 1
	v_cndmask_b32_e64 v35, 0, 64, vcc
	s_cbranch_scc1 .LBB0_158
	v_mov_b32_e32 v1, v4
	v_mov_b32_e32 v3, v0
	v_mov_b32_e32 v5, v2
	v_mov_b32_e32 v7, v10
	v_mov_b32_e32 v9, v6
	v_mov_b32_e32 v11, v8
	v_mov_b32_e32 v13, v12
	v_mov_b32_e32 v15, v18
	v_mov_b32_e32 v17, v14
	v_mov_b32_e32 v19, v16
	v_mov_b32_e32 v21, v20
	v_mov_b32_e32 v23, v26
	v_mov_b32_e32 v25, v22
	v_mov_b32_e32 v27, v24
	v_mov_b32_e32 v29, v28
	v_add_u32_e32 v33, s8, v30
	s_mov_b32 s0, 1
	s_mov_b32 s1, 0
	v_mov_b32_e32 v36, 0
	v_mov_b32_e32 v39, 0
	v_mov_b32_e32 v43, 0
	v_mov_b32_e32 v47, 0
	v_mov_b32_e32 v49, 0
	v_mov_b32_e32 v48, 0
	v_mov_b32_e32 v44, 0
	v_mov_b32_e32 v41, 0
	s_mov_b32 s19, 0
	s_add_i32 s98, s33, 8
	s_and_b32 s98, s98, -8
	s_lshl_b32 s98, s98, 2
.LBB0_156:
	v_add_u32_e32 v50, s1, v33
	v_add_u32_e32 v30, 0x19e00, v50
	ds_read2_b32 v[30:31], v30 offset1:1
	v_cmp_lt_u32_e64 s[12:13], s19, v0
	v_cmp_lt_u32_e64 s[14:15], s0, v3
	s_add_i32 s20, s19, 2
	s_add_i32 s21, s0, 2
	s_waitcnt lgkmcnt(0)
	v_cmp_eq_f32_e64 s[8:9], v30, v4
	v_cmp_eq_f32_e64 s[10:11], v31, v1
	v_cmp_gt_f32_e32 vcc, v31, v1
	v_cmp_gt_f32_e64 s[6:7], v30, v4
	s_and_b64 s[10:11], s[10:11], s[14:15]
	s_and_b64 s[8:9], s[8:9], s[12:13]
	s_or_b64 s[6:7], s[6:7], s[8:9]
	s_or_b64 s[8:9], vcc, s[10:11]
	v_cndmask_b32_e64 v51, 0, 1, s[8:9]
	v_cmp_eq_f32_e64 s[8:9], v30, v2
	v_cmp_eq_f32_e64 s[10:11], v31, v5
	v_cmp_le_u32_e64 s[12:13], s19, v0
	v_cmp_le_u32_e64 s[14:15], s0, v3
	v_cndmask_b32_e64 v52, 0, 1, s[6:7]
	v_cmp_gt_f32_e32 vcc, v31, v5
	v_cmp_gt_f32_e64 s[6:7], v30, v2
	s_and_b64 s[10:11], s[10:11], s[14:15]
	s_and_b64 s[8:9], s[8:9], s[12:13]
	s_or_b64 s[6:7], s[6:7], s[8:9]
	s_or_b64 s[8:9], vcc, s[10:11]
	v_cndmask_b32_e64 v53, 0, 1, s[8:9]
	v_cmp_eq_f32_e64 s[8:9], v30, v10
	v_cmp_eq_f32_e64 s[10:11], v31, v7
	v_cmp_lt_u32_e64 s[12:13], s19, v6
	v_cmp_lt_u32_e64 s[14:15], s0, v9
	v_cndmask_b32_e64 v54, 0, 1, s[6:7]
	v_cmp_gt_f32_e32 vcc, v31, v7
	v_cmp_gt_f32_e64 s[6:7], v30, v10
	s_and_b64 s[10:11], s[10:11], s[14:15]
	s_and_b64 s[8:9], s[8:9], s[12:13]
	s_or_b64 s[6:7], s[6:7], s[8:9]
	s_or_b64 s[8:9], vcc, s[10:11]
	v_cndmask_b32_e64 v55, 0, 1, s[8:9]
	v_cmp_eq_f32_e64 s[8:9], v30, v8
	v_cmp_eq_f32_e64 s[10:11], v31, v11
	v_cmp_lt_u32_e64 s[12:13], s19, v12
	v_cmp_lt_u32_e64 s[14:15], s0, v13
	v_cndmask_b32_e64 v56, 0, 1, s[6:7]
	v_cmp_gt_f32_e32 vcc, v31, v11
	v_cmp_gt_f32_e64 s[6:7], v30, v8
	s_and_b64 s[10:11], s[10:11], s[14:15]
	s_and_b64 s[8:9], s[8:9], s[12:13]
	s_or_b64 s[6:7], s[6:7], s[8:9]
	s_or_b64 s[8:9], vcc, s[10:11]
	v_cndmask_b32_e64 v57, 0, 1, s[8:9]
	v_cmp_eq_f32_e64 s[8:9], v30, v18
	v_cmp_eq_f32_e64 s[10:11], v31, v15
	v_cmp_lt_u32_e64 s[12:13], s19, v14
	v_cmp_lt_u32_e64 s[14:15], s0, v17
	v_cndmask_b32_e64 v58, 0, 1, s[6:7]
	v_cmp_gt_f32_e32 vcc, v31, v15
	v_cmp_gt_f32_e64 s[6:7], v30, v18
	s_and_b64 s[10:11], s[10:11], s[14:15]
	s_and_b64 s[8:9], s[8:9], s[12:13]
	s_or_b64 s[6:7], s[6:7], s[8:9]
	s_or_b64 s[8:9], vcc, s[10:11]
	v_cndmask_b32_e64 v59, 0, 1, s[8:9]
	v_cmp_eq_f32_e64 s[8:9], v30, v16
	v_cmp_eq_f32_e64 s[10:11], v31, v19
	v_cmp_lt_u32_e64 s[12:13], s19, v20
	v_cmp_lt_u32_e64 s[14:15], s0, v21
	v_cndmask_b32_e64 v61, 0, 1, s[6:7]
	v_cmp_gt_f32_e32 vcc, v31, v19
	v_cmp_gt_f32_e64 s[6:7], v30, v16
	s_and_b64 s[10:11], s[10:11], s[14:15]
	s_and_b64 s[8:9], s[8:9], s[12:13]
	s_or_b64 s[6:7], s[6:7], s[8:9]
	s_or_b64 s[8:9], vcc, s[10:11]
	v_cndmask_b32_e64 v62, 0, 1, s[8:9]
	v_cmp_eq_f32_e64 s[8:9], v30, v26
	v_cmp_eq_f32_e64 s[10:11], v31, v23
	v_cmp_lt_u32_e64 s[12:13], s19, v22
	v_cmp_lt_u32_e64 s[14:15], s0, v25
	v_cndmask_b32_e64 v63, 0, 1, s[6:7]
	v_cmp_gt_f32_e32 vcc, v31, v23
	v_cmp_gt_f32_e64 s[6:7], v30, v26
	s_and_b64 s[10:11], s[10:11], s[14:15]
	s_and_b64 s[8:9], s[8:9], s[12:13]
	s_or_b64 s[6:7], s[6:7], s[8:9]
	s_or_b64 s[8:9], vcc, s[10:11]
	v_cndmask_b32_e64 v64, 0, 1, s[8:9]
	v_cndmask_b32_e64 v66, 0, 1, s[6:7]
	v_cmp_gt_f32_e64 s[6:7], v30, v24
	v_cmp_eq_f32_e64 s[8:9], v30, v24
	v_add_u32_e32 v30, 0x19e08, v50
	v_cmp_gt_f32_e32 vcc, v31, v27
	v_cmp_eq_f32_e64 s[10:11], v31, v27
	ds_read2_b32 v[30:31], v30 offset1:1
	v_cmp_lt_u32_e64 s[12:13], s19, v28
	v_cmp_lt_u32_e64 s[14:15], s0, v29
	s_and_b64 s[10:11], s[10:11], s[14:15]
	s_and_b64 s[8:9], s[8:9], s[12:13]
	s_or_b64 s[6:7], s[6:7], s[8:9]
	s_or_b64 s[8:9], vcc, s[10:11]
	v_cndmask_b32_e64 v67, 0, 1, s[8:9]
	s_waitcnt lgkmcnt(0)
; DI void nsa_wg_unit(const Args& a, int l, int b, int g, int tb, unsigned char* lds, int tid_in, bool stage) {
;     ...
;       for (int i = 0; i < 64; ++i) { const float vi = IA[tok * 65 + i];
; #pragma unroll
;           for (int c = 0; c < CPL; ++c) { const int j = qtr * CPL + c; cnt[c] += ((vi > mv[c]) || (vi == mv[c] && i < j)) ? 1 : 0; } }
	v_cmp_eq_f32_e64 s[8:9], v31, v1
	v_cmp_eq_f32_e64 s[10:11], v30, v4
	v_cmp_lt_u32_e64 s[12:13], s21, v3
	v_cmp_lt_u32_e64 s[14:15], s20, v0
	v_cndmask_b32_e64 v68, 0, 1, s[6:7]
	v_cmp_gt_f32_e32 vcc, v30, v4
	v_cmp_gt_f32_e64 s[6:7], v31, v1
	s_and_b64 s[10:11], s[10:11], s[14:15]
	s_and_b64 s[8:9], s[8:9], s[12:13]
	s_or_b64 s[6:7], s[6:7], s[8:9]
	s_or_b64 vcc, vcc, s[10:11]
	v_addc_co_u32_e32 v34, vcc, v34, v52, vcc
	v_addc_co_u32_e64 v41, vcc, v41, v51, s[6:7]
	v_cmp_eq_f32_e64 s[8:9], v31, v5
	v_cmp_eq_f32_e64 s[10:11], v30, v2
	v_cmp_le_u32_e64 s[12:13], s21, v3
	v_cmp_le_u32_e64 s[14:15], s20, v0
	v_cmp_gt_f32_e32 vcc, v30, v2
	v_cmp_gt_f32_e64 s[6:7], v31, v5
	s_and_b64 s[10:11], s[10:11], s[14:15]
	s_and_b64 s[8:9], s[8:9], s[12:13]
	s_or_b64 s[6:7], s[6:7], s[8:9]
	s_or_b64 vcc, vcc, s[10:11]
	v_addc_co_u32_e32 v37, vcc, v37, v54, vcc
	v_addc_co_u32_e64 v44, vcc, v44, v53, s[6:7]
	v_cmp_eq_f32_e64 s[8:9], v31, v7
	v_cmp_eq_f32_e64 s[10:11], v30, v10
	v_cmp_lt_u32_e64 s[12:13], s21, v9
	v_cmp_lt_u32_e64 s[14:15], s20, v6
	v_cmp_gt_f32_e32 vcc, v30, v10
	v_cmp_gt_f32_e64 s[6:7], v31, v7
	s_and_b64 s[10:11], s[10:11], s[14:15]
	s_and_b64 s[8:9], s[8:9], s[12:13]
	s_or_b64 s[6:7], s[6:7], s[8:9]
	s_or_b64 vcc, vcc, s[10:11]
	v_addc_co_u32_e32 v40, vcc, v40, v56, vcc
	v_addc_co_u32_e64 v48, vcc, v48, v55, s[6:7]
	v_cmp_eq_f32_e64 s[8:9], v31, v11
	v_cmp_eq_f32_e64 s[10:11], v30, v8
	v_cmp_lt_u32_e64 s[12:13], s21, v13
	v_cmp_lt_u32_e64 s[14:15], s20, v12
	v_cmp_gt_f32_e32 vcc, v30, v8
	v_cmp_gt_f32_e64 s[6:7], v31, v11
	s_and_b64 s[10:11], s[10:11], s[14:15]
	s_and_b64 s[8:9], s[8:9], s[12:13]
	s_or_b64 s[6:7], s[6:7], s[8:9]
	s_or_b64 vcc, vcc, s[10:11]
	v_addc_co_u32_e32 v45, vcc, v45, v58, vcc
	v_addc_co_u32_e64 v49, vcc, v49, v57, s[6:7]
	v_cmp_eq_f32_e64 s[8:9], v31, v15
	v_cmp_eq_f32_e64 s[10:11], v30, v18
	v_cmp_lt_u32_e64 s[12:13], s21, v17
	v_cmp_lt_u32_e64 s[14:15], s20, v14
	v_cmp_gt_f32_e32 vcc, v30, v18
	v_cmp_gt_f32_e64 s[6:7], v31, v15
	s_and_b64 s[10:11], s[10:11], s[14:15]
	s_and_b64 s[8:9], s[8:9], s[12:13]
	s_or_b64 s[6:7], s[6:7], s[8:9]
	s_or_b64 vcc, vcc, s[10:11]
	v_addc_co_u32_e32 v46, vcc, v46, v61, vcc
	v_addc_co_u32_e64 v47, vcc, v47, v59, s[6:7]
	v_cmp_eq_f32_e64 s[8:9], v31, v19
	v_cmp_eq_f32_e64 s[10:11], v30, v16
	v_cmp_lt_u32_e64 s[12:13], s21, v21
	v_cmp_lt_u32_e64 s[14:15], s20, v20
	v_cmp_gt_f32_e32 vcc, v30, v16
	v_cmp_gt_f32_e64 s[6:7], v31, v19
	s_and_b64 s[10:11], s[10:11], s[14:15]
	s_and_b64 s[8:9], s[8:9], s[12:13]
	s_or_b64 s[6:7], s[6:7], s[8:9]
	s_or_b64 vcc, vcc, s[10:11]
	v_addc_co_u32_e32 v42, vcc, v42, v63, vcc
	v_addc_co_u32_e64 v43, vcc, v43, v62, s[6:7]
	v_cmp_eq_f32_e64 s[8:9], v31, v23
	v_cmp_eq_f32_e64 s[10:11], v30, v26
	v_cmp_lt_u32_e64 s[12:13], s21, v25
	v_cmp_lt_u32_e64 s[14:15], s20, v22
	v_cmp_gt_f32_e32 vcc, v30, v26
	v_cmp_gt_f32_e64 s[6:7], v31, v23
	s_and_b64 s[10:11], s[10:11], s[14:15]
	s_and_b64 s[8:9], s[8:9], s[12:13]
	s_or_b64 s[6:7], s[6:7], s[8:9]
	s_or_b64 vcc, vcc, s[10:11]
	v_addc_co_u32_e32 v38, vcc, v38, v66, vcc
	v_addc_co_u32_e64 v39, vcc, v39, v64, s[6:7]
	v_cmp_gt_f32_e32 vcc, v30, v24
	v_cmp_eq_f32_e64 s[10:11], v30, v24
	v_add_u32_e32 v30, 0x19e10, v50
	v_cmp_gt_f32_e64 s[6:7], v31, v27
	v_cmp_eq_f32_e64 s[8:9], v31, v27
	ds_read2_b32 v[30:31], v30 offset1:1
	v_cmp_lt_u32_e64 s[12:13], s21, v29
	v_cmp_lt_u32_e64 s[14:15], s20, v28
	s_and_b64 s[10:11], s[10:11], s[14:15]
	s_and_b64 s[8:9], s[8:9], s[12:13]
	s_or_b64 s[6:7], s[6:7], s[8:9]
	s_or_b64 vcc, vcc, s[10:11]
	s_add_i32 s20, s19, 4
	s_add_i32 s21, s0, 4
	v_addc_co_u32_e32 v35, vcc, v35, v68, vcc
	v_addc_co_u32_e64 v36, vcc, v36, v67, s[6:7]
	s_waitcnt lgkmcnt(0)
	v_cmp_eq_f32_e64 s[8:9], v31, v1
	v_cmp_eq_f32_e64 s[10:11], v30, v4
	v_cmp_lt_u32_e64 s[12:13], s21, v3
	v_cmp_lt_u32_e64 s[14:15], s20, v0
	v_cmp_gt_f32_e32 vcc, v30, v4
	v_cmp_gt_f32_e64 s[6:7], v31, v1
	s_and_b64 s[10:11], s[10:11], s[14:15]
	s_and_b64 s[8:9], s[8:9], s[12:13]
	s_or_b64 s[6:7], s[6:7], s[8:9]
	s_or_b64 s[8:9], vcc, s[10:11]
	v_cndmask_b32_e64 v62, 0, 1, s[8:9]
	v_cmp_eq_f32_e64 s[8:9], v31, v5
	v_cmp_eq_f32_e64 s[10:11], v30, v2
	v_cmp_le_u32_e64 s[12:13], s21, v3
	v_cmp_le_u32_e64 s[14:15], s20, v0
	v_cndmask_b32_e64 v63, 0, 1, s[6:7]
	v_cmp_gt_f32_e32 vcc, v30, v2
	v_cmp_gt_f32_e64 s[6:7], v31, v5
	s_and_b64 s[10:11], s[10:11], s[14:15]
	s_and_b64 s[8:9], s[8:9], s[12:13]
	s_or_b64 s[6:7], s[6:7], s[8:9]
	s_or_b64 s[8:9], vcc, s[10:11]
	v_cndmask_b32_e64 v57, 0, 1, s[8:9]
	v_cmp_eq_f32_e64 s[8:9], v31, v7
	v_cmp_eq_f32_e64 s[10:11], v30, v10
	v_cmp_lt_u32_e64 s[12:13], s21, v9
	v_cmp_lt_u32_e64 s[14:15], s20, v6
	v_cndmask_b32_e64 v58, 0, 1, s[6:7]
	v_cmp_gt_f32_e32 vcc, v30, v10
	v_cmp_gt_f32_e64 s[6:7], v31, v7
	s_and_b64 s[10:11], s[10:11], s[14:15]
	s_and_b64 s[8:9], s[8:9], s[12:13]
	s_or_b64 s[6:7], s[6:7], s[8:9]
	s_or_b64 s[8:9], vcc, s[10:11]
	v_cndmask_b32_e64 v55, 0, 1, s[8:9]
	v_cmp_eq_f32_e64 s[8:9], v31, v11
	v_cmp_eq_f32_e64 s[10:11], v30, v8
	v_cmp_lt_u32_e64 s[12:13], s21, v13
	v_cmp_lt_u32_e64 s[14:15], s20, v12
	v_cndmask_b32_e64 v56, 0, 1, s[6:7]
	v_cmp_gt_f32_e32 vcc, v30, v8
	v_cmp_gt_f32_e64 s[6:7], v31, v11
	s_and_b64 s[10:11], s[10:11], s[14:15]
	s_and_b64 s[8:9], s[8:9], s[12:13]
	s_or_b64 s[6:7], s[6:7], s[8:9]
	s_or_b64 s[8:9], vcc, s[10:11]
	v_cndmask_b32_e64 v53, 0, 1, s[8:9]
	v_cmp_eq_f32_e64 s[8:9], v31, v15
	v_cmp_eq_f32_e64 s[10:11], v30, v18
	v_cmp_lt_u32_e64 s[12:13], s21, v17
	v_cmp_lt_u32_e64 s[14:15], s20, v14
	v_cndmask_b32_e64 v54, 0, 1, s[6:7]
	v_cmp_gt_f32_e32 vcc, v30, v18
; DI void nsa_wg_unit(const Args& a, int l, int b, int g, int tb, unsigned char* lds, int tid_in, bool stage) {
;     ...
;       for (int i = 0; i < 64; ++i) { const float vi = IA[tok * 65 + i];
; #pragma unroll
;           for (int c = 0; c < CPL; ++c) { const int j = qtr * CPL + c; cnt[c] += ((vi > mv[c]) || (vi == mv[c] && i < j)) ? 1 : 0; } }
	v_cmp_gt_f32_e64 s[6:7], v31, v15
	s_and_b64 s[10:11], s[10:11], s[14:15]
	s_and_b64 s[8:9], s[8:9], s[12:13]
	s_or_b64 s[6:7], s[6:7], s[8:9]
	s_or_b64 s[8:9], vcc, s[10:11]
	v_cndmask_b32_e64 v67, 0, 1, s[8:9]
	v_cmp_eq_f32_e64 s[8:9], v31, v19
	v_cmp_eq_f32_e64 s[10:11], v30, v16
	v_cmp_lt_u32_e64 s[12:13], s21, v21
	v_cmp_lt_u32_e64 s[14:15], s20, v20
	v_cndmask_b32_e64 v68, 0, 1, s[6:7]
	v_cmp_gt_f32_e32 vcc, v30, v16
	v_cmp_gt_f32_e64 s[6:7], v31, v19
	s_and_b64 s[10:11], s[10:11], s[14:15]
	s_and_b64 s[8:9], s[8:9], s[12:13]
	s_or_b64 s[6:7], s[6:7], s[8:9]
	s_or_b64 s[8:9], vcc, s[10:11]
	v_cndmask_b32_e64 v64, 0, 1, s[8:9]
	v_cmp_eq_f32_e64 s[8:9], v31, v23
	v_cmp_eq_f32_e64 s[10:11], v30, v26
	v_cmp_lt_u32_e64 s[12:13], s21, v25
	v_cmp_lt_u32_e64 s[14:15], s20, v22
	v_cndmask_b32_e64 v66, 0, 1, s[6:7]
	v_cmp_gt_f32_e32 vcc, v30, v26
	v_cmp_gt_f32_e64 s[6:7], v31, v23
	s_and_b64 s[10:11], s[10:11], s[14:15]
	s_and_b64 s[8:9], s[8:9], s[12:13]
	s_or_b64 s[6:7], s[6:7], s[8:9]
	s_or_b64 s[8:9], vcc, s[10:11]
	v_cmp_gt_f32_e32 vcc, v30, v24
	v_cmp_eq_f32_e64 s[10:11], v30, v24
	v_add_u32_e32 v30, 0x19e18, v50
	v_cndmask_b32_e64 v59, 0, 1, s[8:9]
	v_cndmask_b32_e64 v61, 0, 1, s[6:7]
	v_cmp_gt_f32_e64 s[6:7], v31, v27
	v_cmp_eq_f32_e64 s[8:9], v31, v27
	ds_read2_b32 v[30:31], v30 offset1:1
	v_cmp_lt_u32_e64 s[12:13], s21, v29
	v_cmp_lt_u32_e64 s[14:15], s20, v28
	s_and_b64 s[10:11], s[10:11], s[14:15]
	s_and_b64 s[8:9], s[8:9], s[12:13]
	s_or_b64 s[6:7], s[6:7], s[8:9]
	s_or_b64 s[8:9], vcc, s[10:11]
	s_add_i32 s20, s0, 6
	s_add_i32 s21, s19, 6
	v_cndmask_b32_e64 v51, 0, 1, s[8:9]
	s_waitcnt lgkmcnt(0)
	v_cmp_eq_f32_e64 s[8:9], v30, v4
	v_cmp_eq_f32_e64 s[12:13], v31, v1
	v_cmp_lt_u32_e64 s[10:11], s21, v0
	v_cmp_lt_u32_e64 s[14:15], s20, v3
	v_cndmask_b32_e64 v52, 0, 1, s[6:7]
	v_cmp_gt_f32_e32 vcc, v31, v1
	v_cmp_gt_f32_e64 s[6:7], v30, v4
	s_and_b64 s[12:13], s[12:13], s[14:15]
	s_and_b64 s[8:9], s[8:9], s[10:11]
	s_or_b64 s[6:7], s[6:7], s[8:9]
	s_or_b64 vcc, vcc, s[12:13]
	v_addc_co_u32_e32 v41, vcc, v41, v63, vcc
	v_addc_co_u32_e64 v34, vcc, v34, v62, s[6:7]
	v_cmp_eq_f32_e64 s[8:9], v30, v2
	v_cmp_eq_f32_e64 s[10:11], v31, v5
	v_cmp_le_u32_e64 s[12:13], s21, v0
	v_cmp_le_u32_e64 s[14:15], s20, v3
	v_cmp_gt_f32_e32 vcc, v31, v5
	v_cmp_gt_f32_e64 s[6:7], v30, v2
	s_and_b64 s[10:11], s[10:11], s[14:15]
	s_and_b64 s[8:9], s[8:9], s[12:13]
	s_or_b64 s[6:7], s[6:7], s[8:9]
	s_or_b64 vcc, vcc, s[10:11]
	v_addc_co_u32_e32 v44, vcc, v44, v58, vcc
	v_addc_co_u32_e64 v37, vcc, v37, v57, s[6:7]
	v_cmp_eq_f32_e64 s[8:9], v30, v10
	v_cmp_eq_f32_e64 s[10:11], v31, v7
	v_cmp_lt_u32_e64 s[12:13], s21, v6
	v_cmp_lt_u32_e64 s[14:15], s20, v9
	v_cmp_gt_f32_e32 vcc, v31, v7
	v_cmp_gt_f32_e64 s[6:7], v30, v10
	s_and_b64 s[10:11], s[10:11], s[14:15]
	s_and_b64 s[8:9], s[8:9], s[12:13]
	s_or_b64 s[6:7], s[6:7], s[8:9]
	s_or_b64 vcc, vcc, s[10:11]
	v_addc_co_u32_e32 v48, vcc, v48, v56, vcc
	v_addc_co_u32_e64 v40, vcc, v40, v55, s[6:7]
	v_cmp_eq_f32_e64 s[8:9], v30, v8
	v_cmp_eq_f32_e64 s[10:11], v31, v11
	v_cmp_lt_u32_e64 s[12:13], s21, v12
	v_cmp_lt_u32_e64 s[14:15], s20, v13
	v_cmp_gt_f32_e32 vcc, v31, v11
	v_cmp_gt_f32_e64 s[6:7], v30, v8
	s_and_b64 s[10:11], s[10:11], s[14:15]
	s_and_b64 s[8:9], s[8:9], s[12:13]
	s_or_b64 s[6:7], s[6:7], s[8:9]
	s_or_b64 vcc, vcc, s[10:11]
	v_addc_co_u32_e32 v49, vcc, v49, v54, vcc
	v_addc_co_u32_e64 v45, vcc, v45, v53, s[6:7]
	v_cmp_eq_f32_e64 s[8:9], v30, v18
	v_cmp_eq_f32_e64 s[10:11], v31, v15
	v_cmp_lt_u32_e64 s[12:13], s21, v14
	v_cmp_lt_u32_e64 s[14:15], s20, v17
	v_cmp_gt_f32_e32 vcc, v31, v15
	v_cmp_gt_f32_e64 s[6:7], v30, v18
	s_and_b64 s[10:11], s[10:11], s[14:15]
	s_and_b64 s[8:9], s[8:9], s[12:13]
	s_or_b64 s[6:7], s[6:7], s[8:9]
	s_or_b64 vcc, vcc, s[10:11]
	v_addc_co_u32_e32 v47, vcc, v47, v68, vcc
	v_addc_co_u32_e64 v46, vcc, v46, v67, s[6:7]
	v_cmp_eq_f32_e64 s[8:9], v30, v16
	v_cmp_eq_f32_e64 s[10:11], v31, v19
	v_cmp_lt_u32_e64 s[12:13], s21, v20
	v_cmp_lt_u32_e64 s[14:15], s20, v21
	v_cmp_gt_f32_e32 vcc, v31, v19
	v_cmp_gt_f32_e64 s[6:7], v30, v16
	s_and_b64 s[10:11], s[10:11], s[14:15]
	s_and_b64 s[8:9], s[8:9], s[12:13]
	s_or_b64 s[6:7], s[6:7], s[8:9]
	s_or_b64 vcc, vcc, s[10:11]
	v_addc_co_u32_e32 v43, vcc, v43, v66, vcc
	v_addc_co_u32_e64 v42, vcc, v42, v64, s[6:7]
	v_cmp_eq_f32_e64 s[8:9], v30, v26
	v_cmp_eq_f32_e64 s[10:11], v31, v23
	v_cmp_lt_u32_e64 s[12:13], s21, v22
	v_cmp_lt_u32_e64 s[14:15], s20, v25
	v_cmp_gt_f32_e32 vcc, v31, v23
	v_cmp_gt_f32_e64 s[6:7], v30, v26
	s_and_b64 s[10:11], s[10:11], s[14:15]
	s_and_b64 s[8:9], s[8:9], s[12:13]
	s_or_b64 s[6:7], s[6:7], s[8:9]
	s_or_b64 vcc, vcc, s[10:11]
	v_addc_co_u32_e32 v39, vcc, v39, v61, vcc
	v_addc_co_u32_e64 v38, vcc, v38, v59, s[6:7]
	v_cmp_eq_f32_e64 s[8:9], v30, v24
	v_cmp_eq_f32_e64 s[10:11], v31, v27
	v_cmp_lt_u32_e64 s[12:13], s21, v28
	v_cmp_lt_u32_e64 s[14:15], s20, v29
	v_cmp_gt_f32_e32 vcc, v31, v27
	v_cmp_gt_f32_e64 s[6:7], v30, v24
	s_and_b64 s[10:11], s[10:11], s[14:15]
	s_and_b64 s[8:9], s[8:9], s[12:13]
	s_or_b64 s[6:7], s[6:7], s[8:9]
	s_or_b64 vcc, vcc, s[10:11]
	s_add_i32 s19, s19, 8
	s_add_i32 s0, s0, 8
	s_add_i32 s1, s1, 32
	v_addc_co_u32_e32 v36, vcc, v36, v52, vcc
	v_addc_co_u32_e64 v35, vcc, v35, v51, s[6:7]
	s_cmp_lg_u32 s1, s98
	s_cbranch_scc1 .LBB0_156
	v_add_u32_e32 v34, v34, v41
	v_add_u32_e32 v37, v37, v44
	v_add_u32_e32 v40, v40, v48
	v_add_u32_e32 v45, v45, v49
	v_add_u32_e32 v46, v46, v47
	v_add_u32_e32 v42, v42, v43
	v_add_u32_e32 v38, v38, v39
	v_add_u32_e32 v35, v35, v36

; #define LDS_FENCE() asm volatile("s_waitcnt lgkmcnt(0)" ::: "memory")
; DI void nsa_wg_unit(const Args& a, int l, int b, int g, int tb, unsigned char* lds, int tid_in, bool stage) {
;     ...
;       LDS_FENCE();
; #pragma unroll
;       for (int c = 0; c < CPL; ++c) IA[tok * 65 + qtr * CPL + c] = mv[c];
;       LDS_FENCE();
;       int cnt[CPL];
; #pragma unroll
;       for (int c = 0; c < CPL; ++c) cnt[c] = (qtr * CPL + c <= jt) ? 0 : 64;
;       if (jt >= 16)
; #pragma unroll 4
;       for (int i = 0; i < 64; ++i) { const float vi = IA[tok * 65 + i];
; #pragma unroll
;           for (int c = 0; c < CPL; ++c) { const int j = qtr * CPL + c; cnt[c] += ((vi > mv[c]) || (vi == mv[c] && i < j)) ? 1 : 0; } }
.LBB0_233:
	s_or_b64 exec, exec, s[0:1]
	v_cmp_lt_u32_e32 vcc, s93, v28
	v_mul_u32_u24_e32 v1, 0x104, v30
	v_lshlrev_b32_e32 v3, 5, v32
	v_cndmask_b32_e64 v34, 0, 64, vcc
	v_cmp_lt_u32_e32 vcc, s93, v22
	v_add3_u32 v1, s9, v1, v3
	s_waitcnt lgkmcnt(0)
	ds_write2_b32 v1, v4, v2 offset1:1
	ds_write2_b32 v1, v10, v8 offset0:2 offset1:3
	ds_write2_b32 v1, v18, v16 offset0:4 offset1:5
	ds_write2_b32 v1, v26, v24 offset0:6 offset1:7
	v_cndmask_b32_e64 v37, 0, 64, vcc
	v_cmp_lt_u32_e32 vcc, s93, v20
	s_waitcnt lgkmcnt(0)
	v_mov_b32_e32 v31, s8
	s_movk_i32 s1, 0x104
	v_cndmask_b32_e64 v41, 0, 64, vcc
	v_cmp_lt_u32_e32 vcc, s93, v14
	s_mov_b32 s0, 0
	v_mov_b32_e32 v1, v24
	v_cndmask_b32_e64 v45, 0, 64, vcc
	v_cmp_lt_u32_e32 vcc, s93, v12
	v_mov_b32_e32 v3, v4
	v_mov_b32_e32 v5, v0
	v_cndmask_b32_e64 v48, 0, 64, vcc
	v_cmp_lt_u32_e32 vcc, s93, v6
	v_mov_b32_e32 v7, v2
	v_mov_b32_e32 v9, v10
	v_cndmask_b32_e64 v44, 0, 64, vcc
	v_cmp_gt_u32_e32 vcc, s93, v0
	v_mov_b32_e32 v11, v6
	v_mov_b32_e32 v13, v8
	v_cndmask_b32_e64 v40, 64, 0, vcc
	v_cmp_lt_u32_e32 vcc, s93, v0
	v_mov_b32_e32 v15, v12
	v_mov_b32_e32 v17, v18
	v_cndmask_b32_e64 v36, 0, 64, vcc
	v_mov_b32_e32 v19, v14
	v_mov_b32_e32 v21, v16
	v_mov_b32_e32 v23, v20
	v_mov_b32_e32 v25, v26
	v_mov_b32_e32 v27, v22
	v_mov_b32_e32 v29, v28
	v_mad_u32_u24 v33, v30, s1, v31
	s_mov_b32 s1, 1
	v_mov_b32_e32 v35, 0
	v_mov_b32_e32 v38, 0
	v_mov_b32_e32 v42, 0
	v_mov_b32_e32 v46, 0
	v_mov_b32_e32 v49, 0
	v_mov_b32_e32 v47, 0
	v_mov_b32_e32 v43, 0
	v_mov_b32_e32 v39, 0
	s_mov_b32 s17, 0
	s_add_i32 s98, s93, 8
	s_and_b32 s98, s98, -8
	s_lshl_b32 s98, s98, 2
.LBB0_234:
	v_add_u32_e32 v50, s0, v33
	v_add_u32_e32 v30, 0x19e00, v50
	ds_read2_b32 v[30:31], v30 offset1:1
	v_cmp_lt_u32_e64 s[12:13], s17, v0
	v_cmp_lt_u32_e64 s[14:15], s1, v5
	s_add_i32 s18, s17, 2
	s_add_i32 s19, s1, 2
	s_waitcnt lgkmcnt(0)
	v_cmp_eq_f32_e64 s[8:9], v30, v4
	v_cmp_eq_f32_e64 s[10:11], v31, v3
	v_cmp_gt_f32_e32 vcc, v31, v3
	v_cmp_gt_f32_e64 s[6:7], v30, v4
	s_and_b64 s[10:11], s[10:11], s[14:15]
	s_and_b64 s[8:9], s[8:9], s[12:13]
	s_or_b64 s[6:7], s[6:7], s[8:9]
	s_or_b64 s[8:9], vcc, s[10:11]
	v_cndmask_b32_e64 v51, 0, 1, s[8:9]
	v_cmp_eq_f32_e64 s[8:9], v30, v2
	v_cmp_eq_f32_e64 s[10:11], v31, v7
	v_cmp_le_u32_e64 s[12:13], s17, v0
	v_cmp_le_u32_e64 s[14:15], s1, v5
	v_cndmask_b32_e64 v52, 0, 1, s[6:7]
	v_cmp_gt_f32_e32 vcc, v31, v7
	v_cmp_gt_f32_e64 s[6:7], v30, v2
	s_and_b64 s[10:11], s[10:11], s[14:15]
	s_and_b64 s[8:9], s[8:9], s[12:13]
	s_or_b64 s[6:7], s[6:7], s[8:9]
	s_or_b64 s[8:9], vcc, s[10:11]
	v_cndmask_b32_e64 v53, 0, 1, s[8:9]
	v_cmp_eq_f32_e64 s[8:9], v30, v10
	v_cmp_eq_f32_e64 s[10:11], v31, v9
	v_cmp_lt_u32_e64 s[12:13], s17, v6
	v_cmp_lt_u32_e64 s[14:15], s1, v11
	v_cndmask_b32_e64 v54, 0, 1, s[6:7]
	v_cmp_gt_f32_e32 vcc, v31, v9
	v_cmp_gt_f32_e64 s[6:7], v30, v10
	s_and_b64 s[10:11], s[10:11], s[14:15]
	s_and_b64 s[8:9], s[8:9], s[12:13]
	s_or_b64 s[6:7], s[6:7], s[8:9]
	s_or_b64 s[8:9], vcc, s[10:11]
	v_cndmask_b32_e64 v55, 0, 1, s[8:9]
	v_cmp_eq_f32_e64 s[8:9], v30, v8
	v_cmp_eq_f32_e64 s[10:11], v31, v13
	v_cmp_lt_u32_e64 s[12:13], s17, v12
	v_cmp_lt_u32_e64 s[14:15], s1, v15
	v_cndmask_b32_e64 v56, 0, 1, s[6:7]
	v_cmp_gt_f32_e32 vcc, v31, v13
	v_cmp_gt_f32_e64 s[6:7], v30, v8
	s_and_b64 s[10:11], s[10:11], s[14:15]
	s_and_b64 s[8:9], s[8:9], s[12:13]
	s_or_b64 s[6:7], s[6:7], s[8:9]
	s_or_b64 s[8:9], vcc, s[10:11]
	v_cndmask_b32_e64 v57, 0, 1, s[8:9]
	v_cmp_eq_f32_e64 s[8:9], v30, v18
	v_cmp_eq_f32_e64 s[10:11], v31, v17
	v_cmp_lt_u32_e64 s[12:13], s17, v14
	v_cmp_lt_u32_e64 s[14:15], s1, v19
	v_cndmask_b32_e64 v58, 0, 1, s[6:7]
	v_cmp_gt_f32_e32 vcc, v31, v17
	v_cmp_gt_f32_e64 s[6:7], v30, v18
	s_and_b64 s[10:11], s[10:11], s[14:15]
	s_and_b64 s[8:9], s[8:9], s[12:13]
	s_or_b64 s[6:7], s[6:7], s[8:9]
	s_or_b64 s[8:9], vcc, s[10:11]
	v_cndmask_b32_e64 v59, 0, 1, s[8:9]
	v_cmp_eq_f32_e64 s[8:9], v30, v16
	v_cmp_eq_f32_e64 s[10:11], v31, v21
	v_cmp_lt_u32_e64 s[12:13], s17, v20
	v_cmp_lt_u32_e64 s[14:15], s1, v23
	v_cndmask_b32_e64 v61, 0, 1, s[6:7]
	v_cmp_gt_f32_e32 vcc, v31, v21
	v_cmp_gt_f32_e64 s[6:7], v30, v16
	s_and_b64 s[10:11], s[10:11], s[14:15]
	s_and_b64 s[8:9], s[8:9], s[12:13]
	s_or_b64 s[6:7], s[6:7], s[8:9]
	s_or_b64 s[8:9], vcc, s[10:11]
	v_cndmask_b32_e64 v62, 0, 1, s[8:9]
	v_cmp_eq_f32_e64 s[8:9], v30, v26
	v_cmp_eq_f32_e64 s[10:11], v31, v25
	v_cmp_lt_u32_e64 s[12:13], s17, v22
	v_cmp_lt_u32_e64 s[14:15], s1, v27
	v_cndmask_b32_e64 v63, 0, 1, s[6:7]
	v_cmp_gt_f32_e32 vcc, v31, v25
	v_cmp_gt_f32_e64 s[6:7], v30, v26
	s_and_b64 s[10:11], s[10:11], s[14:15]
	s_and_b64 s[8:9], s[8:9], s[12:13]
	s_or_b64 s[6:7], s[6:7], s[8:9]
	s_or_b64 s[8:9], vcc, s[10:11]
	v_cndmask_b32_e64 v64, 0, 1, s[8:9]
	v_cndmask_b32_e64 v66, 0, 1, s[6:7]
	v_cmp_gt_f32_e64 s[6:7], v30, v24
	v_cmp_eq_f32_e64 s[8:9], v30, v24
	v_add_u32_e32 v30, 0x19e08, v50
	v_cmp_gt_f32_e32 vcc, v31, v1
	v_cmp_eq_f32_e64 s[10:11], v31, v1
	ds_read2_b32 v[30:31], v30 offset1:1
	v_cmp_lt_u32_e64 s[12:13], s17, v28
	v_cmp_lt_u32_e64 s[14:15], s1, v29
	s_and_b64 s[10:11], s[10:11], s[14:15]
	s_and_b64 s[8:9], s[8:9], s[12:13]
	s_or_b64 s[6:7], s[6:7], s[8:9]
	s_or_b64 s[8:9], vcc, s[10:11]
	v_cndmask_b32_e64 v67, 0, 1, s[8:9]
	s_waitcnt lgkmcnt(0)
; DI void nsa_wg_unit(const Args& a, int l, int b, int g, int tb, unsigned char* lds, int tid_in, bool stage) {
;     ...
;       for (int i = 0; i < 64; ++i) { const float vi = IA[tok * 65 + i];
; #pragma unroll
;           for (int c = 0; c < CPL; ++c) { const int j = qtr * CPL + c; cnt[c] += ((vi > mv[c]) || (vi == mv[c] && i < j)) ? 1 : 0; } }
	v_cmp_eq_f32_e64 s[8:9], v31, v3
	v_cmp_eq_f32_e64 s[10:11], v30, v4
	v_cmp_lt_u32_e64 s[12:13], s19, v5
	v_cmp_lt_u32_e64 s[14:15], s18, v0
	v_cndmask_b32_e64 v68, 0, 1, s[6:7]
	v_cmp_gt_f32_e32 vcc, v30, v4
	v_cmp_gt_f32_e64 s[6:7], v31, v3
	s_and_b64 s[10:11], s[10:11], s[14:15]
	s_and_b64 s[8:9], s[8:9], s[12:13]
	s_or_b64 s[6:7], s[6:7], s[8:9]
	s_or_b64 vcc, vcc, s[10:11]
	v_addc_co_u32_e32 v36, vcc, v36, v52, vcc
	v_addc_co_u32_e64 v39, vcc, v39, v51, s[6:7]
	v_cmp_eq_f32_e64 s[8:9], v31, v7
	v_cmp_eq_f32_e64 s[10:11], v30, v2
	v_cmp_le_u32_e64 s[12:13], s19, v5
	v_cmp_le_u32_e64 s[14:15], s18, v0
	v_cmp_gt_f32_e32 vcc, v30, v2
	v_cmp_gt_f32_e64 s[6:7], v31, v7
	s_and_b64 s[10:11], s[10:11], s[14:15]
	s_and_b64 s[8:9], s[8:9], s[12:13]
	s_or_b64 s[6:7], s[6:7], s[8:9]
	s_or_b64 vcc, vcc, s[10:11]
	v_addc_co_u32_e32 v40, vcc, v40, v54, vcc
	v_addc_co_u32_e64 v43, vcc, v43, v53, s[6:7]
	v_cmp_eq_f32_e64 s[8:9], v31, v9
	v_cmp_eq_f32_e64 s[10:11], v30, v10
	v_cmp_lt_u32_e64 s[12:13], s19, v11
	v_cmp_lt_u32_e64 s[14:15], s18, v6
	v_cmp_gt_f32_e32 vcc, v30, v10
	v_cmp_gt_f32_e64 s[6:7], v31, v9
	s_and_b64 s[10:11], s[10:11], s[14:15]
	s_and_b64 s[8:9], s[8:9], s[12:13]
	s_or_b64 s[6:7], s[6:7], s[8:9]
	s_or_b64 vcc, vcc, s[10:11]
	v_addc_co_u32_e32 v44, vcc, v44, v56, vcc
	v_addc_co_u32_e64 v47, vcc, v47, v55, s[6:7]
	v_cmp_eq_f32_e64 s[8:9], v31, v13
	v_cmp_eq_f32_e64 s[10:11], v30, v8
	v_cmp_lt_u32_e64 s[12:13], s19, v15
	v_cmp_lt_u32_e64 s[14:15], s18, v12
	v_cmp_gt_f32_e32 vcc, v30, v8
	v_cmp_gt_f32_e64 s[6:7], v31, v13
	s_and_b64 s[10:11], s[10:11], s[14:15]
	s_and_b64 s[8:9], s[8:9], s[12:13]
	s_or_b64 s[6:7], s[6:7], s[8:9]
	s_or_b64 vcc, vcc, s[10:11]
	v_addc_co_u32_e32 v48, vcc, v48, v58, vcc
	v_addc_co_u32_e64 v49, vcc, v49, v57, s[6:7]
	v_cmp_eq_f32_e64 s[8:9], v31, v17
	v_cmp_eq_f32_e64 s[10:11], v30, v18
	v_cmp_lt_u32_e64 s[12:13], s19, v19
	v_cmp_lt_u32_e64 s[14:15], s18, v14
	v_cmp_gt_f32_e32 vcc, v30, v18
	v_cmp_gt_f32_e64 s[6:7], v31, v17
	s_and_b64 s[10:11], s[10:11], s[14:15]
	s_and_b64 s[8:9], s[8:9], s[12:13]
	s_or_b64 s[6:7], s[6:7], s[8:9]
	s_or_b64 vcc, vcc, s[10:11]
	v_addc_co_u32_e32 v45, vcc, v45, v61, vcc
	v_addc_co_u32_e64 v46, vcc, v46, v59, s[6:7]
	v_cmp_eq_f32_e64 s[8:9], v31, v21
	v_cmp_eq_f32_e64 s[10:11], v30, v16
	v_cmp_lt_u32_e64 s[12:13], s19, v23
	v_cmp_lt_u32_e64 s[14:15], s18, v20
	v_cmp_gt_f32_e32 vcc, v30, v16
	v_cmp_gt_f32_e64 s[6:7], v31, v21
	s_and_b64 s[10:11], s[10:11], s[14:15]
	s_and_b64 s[8:9], s[8:9], s[12:13]
	s_or_b64 s[6:7], s[6:7], s[8:9]
	s_or_b64 vcc, vcc, s[10:11]
	v_addc_co_u32_e32 v41, vcc, v41, v63, vcc
	v_addc_co_u32_e64 v42, vcc, v42, v62, s[6:7]
	v_cmp_eq_f32_e64 s[8:9], v31, v25
	v_cmp_eq_f32_e64 s[10:11], v30, v26
	v_cmp_lt_u32_e64 s[12:13], s19, v27
	v_cmp_lt_u32_e64 s[14:15], s18, v22
	v_cmp_gt_f32_e32 vcc, v30, v26
	v_cmp_gt_f32_e64 s[6:7], v31, v25
	s_and_b64 s[10:11], s[10:11], s[14:15]
	s_and_b64 s[8:9], s[8:9], s[12:13]
	s_or_b64 s[6:7], s[6:7], s[8:9]
	s_or_b64 vcc, vcc, s[10:11]
	v_addc_co_u32_e32 v37, vcc, v37, v66, vcc
	v_addc_co_u32_e64 v38, vcc, v38, v64, s[6:7]
	v_cmp_gt_f32_e32 vcc, v30, v24
	v_cmp_eq_f32_e64 s[10:11], v30, v24
	v_add_u32_e32 v30, 0x19e10, v50
	v_cmp_gt_f32_e64 s[6:7], v31, v1
	v_cmp_eq_f32_e64 s[8:9], v31, v1
	ds_read2_b32 v[30:31], v30 offset1:1
	v_cmp_lt_u32_e64 s[12:13], s19, v29
	v_cmp_lt_u32_e64 s[14:15], s18, v28
	s_and_b64 s[10:11], s[10:11], s[14:15]
	s_and_b64 s[8:9], s[8:9], s[12:13]
	s_or_b64 s[6:7], s[6:7], s[8:9]
	s_or_b64 vcc, vcc, s[10:11]
	s_add_i32 s18, s17, 4
	s_add_i32 s19, s1, 4
	v_addc_co_u32_e32 v34, vcc, v34, v68, vcc
	v_addc_co_u32_e64 v35, vcc, v35, v67, s[6:7]
	s_waitcnt lgkmcnt(0)
	v_cmp_eq_f32_e64 s[8:9], v31, v3
	v_cmp_eq_f32_e64 s[10:11], v30, v4
	v_cmp_lt_u32_e64 s[12:13], s19, v5
	v_cmp_lt_u32_e64 s[14:15], s18, v0
	v_cmp_gt_f32_e32 vcc, v30, v4
	v_cmp_gt_f32_e64 s[6:7], v31, v3
	s_and_b64 s[10:11], s[10:11], s[14:15]
	s_and_b64 s[8:9], s[8:9], s[12:13]
	s_or_b64 s[6:7], s[6:7], s[8:9]
	s_or_b64 s[8:9], vcc, s[10:11]
	v_cndmask_b32_e64 v62, 0, 1, s[8:9]
	v_cmp_eq_f32_e64 s[8:9], v31, v7
	v_cmp_eq_f32_e64 s[10:11], v30, v2
	v_cmp_le_u32_e64 s[12:13], s19, v5
	v_cmp_le_u32_e64 s[14:15], s18, v0
	v_cndmask_b32_e64 v63, 0, 1, s[6:7]
	v_cmp_gt_f32_e32 vcc, v30, v2
	v_cmp_gt_f32_e64 s[6:7], v31, v7
	s_and_b64 s[10:11], s[10:11], s[14:15]
	s_and_b64 s[8:9], s[8:9], s[12:13]
	s_or_b64 s[6:7], s[6:7], s[8:9]
	s_or_b64 s[8:9], vcc, s[10:11]
	v_cndmask_b32_e64 v57, 0, 1, s[8:9]
	v_cmp_eq_f32_e64 s[8:9], v31, v9
	v_cmp_eq_f32_e64 s[10:11], v30, v10
	v_cmp_lt_u32_e64 s[12:13], s19, v11
	v_cmp_lt_u32_e64 s[14:15], s18, v6
	v_cndmask_b32_e64 v58, 0, 1, s[6:7]
	v_cmp_gt_f32_e32 vcc, v30, v10
	v_cmp_gt_f32_e64 s[6:7], v31, v9
	s_and_b64 s[10:11], s[10:11], s[14:15]
	s_and_b64 s[8:9], s[8:9], s[12:13]
	s_or_b64 s[6:7], s[6:7], s[8:9]
	s_or_b64 s[8:9], vcc, s[10:11]
	v_cndmask_b32_e64 v55, 0, 1, s[8:9]
	v_cmp_eq_f32_e64 s[8:9], v31, v13
	v_cmp_eq_f32_e64 s[10:11], v30, v8
	v_cmp_lt_u32_e64 s[12:13], s19, v15
	v_cmp_lt_u32_e64 s[14:15], s18, v12
	v_cndmask_b32_e64 v56, 0, 1, s[6:7]
	v_cmp_gt_f32_e32 vcc, v30, v8
	v_cmp_gt_f32_e64 s[6:7], v31, v13
	s_and_b64 s[10:11], s[10:11], s[14:15]
	s_and_b64 s[8:9], s[8:9], s[12:13]
	s_or_b64 s[6:7], s[6:7], s[8:9]
	s_or_b64 s[8:9], vcc, s[10:11]
	v_cndmask_b32_e64 v53, 0, 1, s[8:9]
	v_cmp_eq_f32_e64 s[8:9], v31, v17
	v_cmp_eq_f32_e64 s[10:11], v30, v18
	v_cmp_lt_u32_e64 s[12:13], s19, v19
	v_cmp_lt_u32_e64 s[14:15], s18, v14
	v_cndmask_b32_e64 v54, 0, 1, s[6:7]
	v_cmp_gt_f32_e32 vcc, v30, v18
	v_cmp_gt_f32_e64 s[6:7], v31, v17
	s_and_b64 s[10:11], s[10:11], s[14:15]
; DI void nsa_wg_unit(const Args& a, int l, int b, int g, int tb, unsigned char* lds, int tid_in, bool stage) {
;     ...
;       for (int i = 0; i < 64; ++i) { const float vi = IA[tok * 65 + i];
; #pragma unroll
;           for (int c = 0; c < CPL; ++c) { const int j = qtr * CPL + c; cnt[c] += ((vi > mv[c]) || (vi == mv[c] && i < j)) ? 1 : 0; } }
	s_and_b64 s[8:9], s[8:9], s[12:13]
	s_or_b64 s[6:7], s[6:7], s[8:9]
	s_or_b64 s[8:9], vcc, s[10:11]
	v_cndmask_b32_e64 v67, 0, 1, s[8:9]
	v_cmp_eq_f32_e64 s[8:9], v31, v21
	v_cmp_eq_f32_e64 s[10:11], v30, v16
	v_cmp_lt_u32_e64 s[12:13], s19, v23
	v_cmp_lt_u32_e64 s[14:15], s18, v20
	v_cndmask_b32_e64 v68, 0, 1, s[6:7]
	v_cmp_gt_f32_e32 vcc, v30, v16
	v_cmp_gt_f32_e64 s[6:7], v31, v21
	s_and_b64 s[10:11], s[10:11], s[14:15]
	s_and_b64 s[8:9], s[8:9], s[12:13]
	s_or_b64 s[6:7], s[6:7], s[8:9]
	s_or_b64 s[8:9], vcc, s[10:11]
	v_cndmask_b32_e64 v64, 0, 1, s[8:9]
	v_cmp_eq_f32_e64 s[8:9], v31, v25
	v_cmp_eq_f32_e64 s[10:11], v30, v26
	v_cmp_lt_u32_e64 s[12:13], s19, v27
	v_cmp_lt_u32_e64 s[14:15], s18, v22
	v_cndmask_b32_e64 v66, 0, 1, s[6:7]
	v_cmp_gt_f32_e32 vcc, v30, v26
	v_cmp_gt_f32_e64 s[6:7], v31, v25
	s_and_b64 s[10:11], s[10:11], s[14:15]
	s_and_b64 s[8:9], s[8:9], s[12:13]
	s_or_b64 s[6:7], s[6:7], s[8:9]
	s_or_b64 s[8:9], vcc, s[10:11]
	v_cmp_gt_f32_e32 vcc, v30, v24
	v_cmp_eq_f32_e64 s[10:11], v30, v24
	v_add_u32_e32 v30, 0x19e18, v50
	v_cndmask_b32_e64 v59, 0, 1, s[8:9]
	v_cndmask_b32_e64 v61, 0, 1, s[6:7]
	v_cmp_gt_f32_e64 s[6:7], v31, v1
	v_cmp_eq_f32_e64 s[8:9], v31, v1
	ds_read2_b32 v[30:31], v30 offset1:1
	v_cmp_lt_u32_e64 s[12:13], s19, v29
	v_cmp_lt_u32_e64 s[14:15], s18, v28
	s_and_b64 s[10:11], s[10:11], s[14:15]
	s_and_b64 s[8:9], s[8:9], s[12:13]
	s_or_b64 s[6:7], s[6:7], s[8:9]
	s_or_b64 s[8:9], vcc, s[10:11]
	s_add_i32 s18, s1, 6
	s_add_i32 s19, s17, 6
	v_cndmask_b32_e64 v51, 0, 1, s[8:9]
	s_waitcnt lgkmcnt(0)
	v_cmp_eq_f32_e64 s[8:9], v30, v4
	v_cmp_eq_f32_e64 s[12:13], v31, v3
	v_cmp_lt_u32_e64 s[10:11], s19, v0
	v_cmp_lt_u32_e64 s[14:15], s18, v5
	v_cndmask_b32_e64 v52, 0, 1, s[6:7]
	v_cmp_gt_f32_e32 vcc, v31, v3
	v_cmp_gt_f32_e64 s[6:7], v30, v4
	s_and_b64 s[12:13], s[12:13], s[14:15]
	s_and_b64 s[8:9], s[8:9], s[10:11]
	s_or_b64 s[6:7], s[6:7], s[8:9]
	s_or_b64 vcc, vcc, s[12:13]
	v_addc_co_u32_e32 v39, vcc, v39, v63, vcc
	v_addc_co_u32_e64 v36, vcc, v36, v62, s[6:7]
	v_cmp_eq_f32_e64 s[8:9], v30, v2
	v_cmp_eq_f32_e64 s[10:11], v31, v7
	v_cmp_le_u32_e64 s[12:13], s19, v0
	v_cmp_le_u32_e64 s[14:15], s18, v5
	v_cmp_gt_f32_e32 vcc, v31, v7
	v_cmp_gt_f32_e64 s[6:7], v30, v2
	s_and_b64 s[10:11], s[10:11], s[14:15]
	s_and_b64 s[8:9], s[8:9], s[12:13]
	s_or_b64 s[6:7], s[6:7], s[8:9]
	s_or_b64 vcc, vcc, s[10:11]
	v_addc_co_u32_e32 v43, vcc, v43, v58, vcc
	v_addc_co_u32_e64 v40, vcc, v40, v57, s[6:7]
	v_cmp_eq_f32_e64 s[8:9], v30, v10
	v_cmp_eq_f32_e64 s[10:11], v31, v9
	v_cmp_lt_u32_e64 s[12:13], s19, v6
	v_cmp_lt_u32_e64 s[14:15], s18, v11
	v_cmp_gt_f32_e32 vcc, v31, v9
	v_cmp_gt_f32_e64 s[6:7], v30, v10
	s_and_b64 s[10:11], s[10:11], s[14:15]
	s_and_b64 s[8:9], s[8:9], s[12:13]
	s_or_b64 s[6:7], s[6:7], s[8:9]
	s_or_b64 vcc, vcc, s[10:11]
	v_addc_co_u32_e32 v47, vcc, v47, v56, vcc
	v_addc_co_u32_e64 v44, vcc, v44, v55, s[6:7]
	v_cmp_eq_f32_e64 s[8:9], v30, v8
	v_cmp_eq_f32_e64 s[10:11], v31, v13
	v_cmp_lt_u32_e64 s[12:13], s19, v12
	v_cmp_lt_u32_e64 s[14:15], s18, v15
	v_cmp_gt_f32_e32 vcc, v31, v13
	v_cmp_gt_f32_e64 s[6:7], v30, v8
	s_and_b64 s[10:11], s[10:11], s[14:15]
	s_and_b64 s[8:9], s[8:9], s[12:13]
	s_or_b64 s[6:7], s[6:7], s[8:9]
	s_or_b64 vcc, vcc, s[10:11]
	v_addc_co_u32_e32 v49, vcc, v49, v54, vcc
	v_addc_co_u32_e64 v48, vcc, v48, v53, s[6:7]
	v_cmp_eq_f32_e64 s[8:9], v30, v18
	v_cmp_eq_f32_e64 s[10:11], v31, v17
	v_cmp_lt_u32_e64 s[12:13], s19, v14
	v_cmp_lt_u32_e64 s[14:15], s18, v19
	v_cmp_gt_f32_e32 vcc, v31, v17
	v_cmp_gt_f32_e64 s[6:7], v30, v18
	s_and_b64 s[10:11], s[10:11], s[14:15]
	s_and_b64 s[8:9], s[8:9], s[12:13]
	s_or_b64 s[6:7], s[6:7], s[8:9]
	s_or_b64 vcc, vcc, s[10:11]
	v_addc_co_u32_e32 v46, vcc, v46, v68, vcc
	v_addc_co_u32_e64 v45, vcc, v45, v67, s[6:7]
	v_cmp_eq_f32_e64 s[8:9], v30, v16
	v_cmp_eq_f32_e64 s[10:11], v31, v21
	v_cmp_lt_u32_e64 s[12:13], s19, v20
	v_cmp_lt_u32_e64 s[14:15], s18, v23
	v_cmp_gt_f32_e32 vcc, v31, v21
	v_cmp_gt_f32_e64 s[6:7], v30, v16
	s_and_b64 s[10:11], s[10:11], s[14:15]
	s_and_b64 s[8:9], s[8:9], s[12:13]
	s_or_b64 s[6:7], s[6:7], s[8:9]
	s_or_b64 vcc, vcc, s[10:11]
	v_addc_co_u32_e32 v42, vcc, v42, v66, vcc
	v_addc_co_u32_e64 v41, vcc, v41, v64, s[6:7]
	v_cmp_eq_f32_e64 s[8:9], v30, v26
	v_cmp_eq_f32_e64 s[10:11], v31, v25
	v_cmp_lt_u32_e64 s[12:13], s19, v22
	v_cmp_lt_u32_e64 s[14:15], s18, v27
	v_cmp_gt_f32_e32 vcc, v31, v25
	v_cmp_gt_f32_e64 s[6:7], v30, v26
	s_and_b64 s[10:11], s[10:11], s[14:15]
	s_and_b64 s[8:9], s[8:9], s[12:13]
	s_or_b64 s[6:7], s[6:7], s[8:9]
	s_or_b64 vcc, vcc, s[10:11]
	v_addc_co_u32_e32 v38, vcc, v38, v61, vcc
	v_addc_co_u32_e64 v37, vcc, v37, v59, s[6:7]
	v_cmp_eq_f32_e64 s[8:9], v30, v24
	v_cmp_eq_f32_e64 s[10:11], v31, v1
	v_cmp_lt_u32_e64 s[12:13], s19, v28
	v_cmp_lt_u32_e64 s[14:15], s18, v29
	v_cmp_gt_f32_e32 vcc, v31, v1
	v_cmp_gt_f32_e64 s[6:7], v30, v24
	s_and_b64 s[10:11], s[10:11], s[14:15]
	s_and_b64 s[8:9], s[8:9], s[12:13]
	s_or_b64 s[6:7], s[6:7], s[8:9]
	s_or_b64 vcc, vcc, s[10:11]
	s_add_i32 s17, s17, 8
	s_add_i32 s1, s1, 8
	s_add_i32 s0, s0, 32
	v_addc_co_u32_e32 v35, vcc, v35, v52, vcc
	v_addc_co_u32_e64 v34, vcc, v34, v51, s[6:7]
	s_cmp_lg_u32 s0, s98
	s_cbranch_scc1 .LBB0_234
; DI void nsa_wg_unit(const Args& a, int l, int b, int g, int tb, unsigned char* lds, int tid_in, bool stage) {
;     ...
;       unsigned mc = 0;
; #pragma unroll
;       for (int c = 0; c < CPL; ++c) mc |= (cnt[c] < 16) ? (1u << c) : 0u;
;       unsigned lo = 0, hi = 0;
; #pragma unroll
;       for (int k = 0; k < LPT / 2; ++k) { lo |= (unsigned)__shfl((int)mc, tok * LPT + k) << (CPL * k); hi |= (unsigned)__shfl((int)mc, tok * LPT + LPT / 2 + k) << (CPL * k); }
;       { const int src = (rl >> 2) * LPT; sel_lo[0] = (unsigned)__shfl((int)lo, src); sel_hi[0] = (unsigned)__shfl((int)hi, src); }
;       unsigned ul = lo, uh = hi;
; #pragma unroll
;       for (int o = LPT; o < 64; o <<= 1) { ul |= (unsigned)__shfl_xor((int)ul, o); uh |= (unsigned)__shfl_xor((int)uh, o); }
;       ulo = (unsigned)__builtin_amdgcn_readfirstlane((int)ul); uhi = (unsigned)__builtin_amdgcn_readfirstlane((int)uh); }
;     const unsigned long long myu = ((unsigned long long)uhi << 32) | (unsigned long long)ulo;
;     unsigned long long* UW = (unsigned long long*)(lds + AL_UW);
;     if (lane == 0) UW[wave] = myu;
;     __syncthreads();
;     unsigned long long wgu = 0ull;
; #pragma unroll
;     for (int w = 0; w < 8; ++w) wgu |= UW[w];
;     wgu = ((unsigned long long)(unsigned)__builtin_amdgcn_readfirstlane((int)(wgu >> 32)) << 32) | (unsigned long long)(unsigned)__builtin_amdgcn_readfirstlane((int)(unsigned)wgu);
;     const int srow = tid >> 3, sch = tid & 7;
;     const LP kfl = L + AL_KR + rl * KR_PB + 16 * h, vfl = L + AL_VR + rl * VR_PB + 8 * h;
;     attn_reset(st);
;     { unsigned long long rem = wgu & ((jt >= 63) ? ~0ull : ((1ull << (jt + 1)) - 1ull));
;       const unsigned koff = (unsigned)(srow * ZP + sch * 8) * 2u, voff = (unsigned)(srow * SEQ + sch * 8) * 2u;
;       const char* kgb = (const char*)(zb + C_KV + 2 * 128 + g * 64); const char* vgb = (const char*)VST;
;       int j = rem ? (int)__builtin_ctzll(rem) : -1, bi = 0; u32x4 kreg, vreg;
;       if (j >= 0) { kreg = *(const u32x4*)(kgb + (size_t)(64 * j) * ZP * 2 + koff); vreg = *(const u32x4*)(vgb + (size_t)(64 * j) * 2 + voff);
;           *(u32x4*)(lds + AL_KR + srow * KR_PB + sch * 16) = kreg; u32x2* d = (u32x2*)(lds + AL_VR + srow * VR_PB + sch * 16); u32x2 lo2, hi2; lo2.x = vreg.x; lo2.y = vreg.y; hi2.x = vreg.z; hi2.y = vreg.w; d[0] = lo2; d[1] = hi2; }
;       __syncthreads();
	v_add_u32_e32 v0, v36, v39
	v_add_u32_e32 v1, v40, v43
	v_cmp_gt_i32_e32 vcc, 16, v0
	v_add_u32_e32 v2, v44, v47
	v_add_u32_e32 v3, v48, v49
	v_cndmask_b32_e64 v0, 0, 1, vcc
	v_cmp_gt_i32_e32 vcc, 16, v1
	v_add_u32_e32 v4, v45, v46
	v_add_u32_e32 v5, v41, v42
	v_cndmask_b32_e64 v1, 0, 2, vcc
	v_cmp_gt_i32_e32 vcc, 16, v2
	v_or_b32_e32 v0, v1, v0
	v_add_u32_e32 v6, v37, v38
	v_cndmask_b32_e64 v1, 0, 4, vcc
	v_cmp_gt_i32_e32 vcc, 16, v3
	v_add_u32_e32 v7, v34, v35
	s_nop 0
	v_cndmask_b32_e64 v2, 0, 8, vcc
	v_cmp_gt_i32_e32 vcc, 16, v4
	v_or3_b32 v0, v0, v1, v2
	s_nop 0
	v_cndmask_b32_e64 v1, 0, 16, vcc
	v_cmp_gt_i32_e32 vcc, 16, v5
	s_nop 1
	v_cndmask_b32_e64 v2, 0, 32, vcc
	v_cmp_gt_i32_e32 vcc, 16, v6
	v_or3_b32 v0, v0, v1, v2
	s_nop 0
	v_cndmask_b32_e64 v1, 0, 64, vcc
	v_cmp_gt_i32_e32 vcc, 16, v7
	s_nop 1
	v_cndmask_b32_e32 v2, 0, v198, vcc
	v_or3_b32 v0, v0, v1, v2
	v_and_or_b32 v1, v74, 56, v149
	v_lshlrev_b32_e32 v1, 2, v1
	ds_bpermute_b32 v2, v1, v0
	ds_bpermute_b32 v3, v1, v0 offset:4
	ds_bpermute_b32 v4, v1, v0 offset:16
	ds_bpermute_b32 v5, v1, v0 offset:20
	ds_bpermute_b32 v6, v1, v0 offset:24
	ds_bpermute_b32 v7, v1, v0 offset:12
	s_waitcnt lgkmcnt(4)
	v_lshl_or_b32 v2, v3, 8, v2
	ds_bpermute_b32 v3, v1, v0 offset:8
	ds_bpermute_b32 v0, v1, v0 offset:28
	s_waitcnt lgkmcnt(4)
	v_lshl_or_b32 v4, v5, 8, v4
	s_waitcnt lgkmcnt(2)
	v_lshlrev_b32_e32 v5, 24, v7
	v_cmp_eq_u32_e32 vcc, 0, v76
	s_waitcnt lgkmcnt(1)
	v_lshlrev_b32_e32 v1, 16, v3
	v_lshlrev_b32_e32 v3, 16, v6
	s_waitcnt lgkmcnt(0)
	v_lshlrev_b32_e32 v0, 24, v0
	v_or3_b32 v1, v2, v1, v5
	v_or3_b32 v0, v4, v3, v0
	ds_bpermute_b32 v2, v150, v1
	ds_bpermute_b32 v3, v150, v0
	v_lshl_or_b32 v6, v75, 5, v155
	ds_bpermute_b32 v159, v6, v1
	ds_bpermute_b32 v165, v6, v0
	s_waitcnt lgkmcnt(3)
	v_or_b32_e32 v2, v2, v1
	s_waitcnt lgkmcnt(2)
	v_or_b32_e32 v3, v3, v0
	ds_bpermute_b32 v4, v151, v2
	ds_bpermute_b32 v5, v151, v3
	s_waitcnt lgkmcnt(1)
	v_or_b32_e32 v2, v4, v2
	s_waitcnt lgkmcnt(0)
	v_or_b32_e32 v3, v5, v3
	ds_bpermute_b32 v4, v148, v2
	ds_bpermute_b32 v5, v148, v3
	s_waitcnt lgkmcnt(1)
	v_or_b32_e32 v1, v4, v2
	s_waitcnt lgkmcnt(0)
	v_or_b32_e32 v0, v5, v3
	v_readfirstlane_b32 s0, v1
	v_readfirstlane_b32 s1, v0
	s_and_saveexec_b64 s[6:7], vcc
	s_add_i32 s8, s16, 0
	s_add_i32 s8, s8, 0x22200
	v_mov_b32_e32 v0, s8
	v_mov_b64_e32 v[2:3], s[0:1]
	ds_write_b64 v0, v[2:3]
	s_or_b64 exec, exec, s[6:7]
	v_mov_b32_e32 v0, s44
	s_waitcnt lgkmcnt(0)
	s_barrier
	ds_read_b128 v[0:3], v0
	v_readlane_b32 s6, v253, 24
	s_sub_i32 s8, 64, s33
	s_lshl_b64 s[8:9], -1, s8
	s_not_b64 s[8:9], s[8:9]
	s_waitcnt lgkmcnt(0)
	v_or_b32_e32 v4, v2, v0
	v_mov_b32_e32 v0, s6
	v_or_b32_e32 v5, v3, v1
	ds_read_b128 v[0:3], v0
	v_readlane_b32 s6, v253, 25
	s_cmp_lg_u32 s33, 0
	s_cselect_b32 s9, s9, -1
	s_cselect_b32 s8, s8, -1
	s_waitcnt lgkmcnt(0)
	v_or_b32_e32 v0, v4, v0
	v_or_b32_e32 v1, v5, v1
	v_or_b32_e32 v4, v0, v2
	v_mov_b32_e32 v0, s6
	v_or_b32_e32 v5, v1, v3
	ds_read_b128 v[0:3], v0
	v_readlane_b32 s6, v253, 26
	v_lshlrev_b32_e32 v138, 4, v32
	s_waitcnt lgkmcnt(0)
	v_or_b32_e32 v0, v4, v0
	v_or_b32_e32 v1, v5, v1
	v_or_b32_e32 v4, v0, v2
	v_mov_b32_e32 v0, s6
	v_or_b32_e32 v5, v1, v3
	ds_read_b128 v[0:3], v0
	s_waitcnt lgkmcnt(0)
	v_or_b32_e32 v0, v4, v0
	v_or_b32_e32 v1, v5, v1
	v_or_b32_e32 v0, v0, v2
	v_or_b32_e32 v1, v1, v3
	v_readfirstlane_b32 s6, v0
	v_readfirstlane_b32 s7, v1
	v_ashrrev_i32_e32 v0, 3, v74
	s_and_b64 s[78:79], s[6:7], s[8:9]
	s_waitcnt vmcnt(8)
	v_mad_u64_u32 v[142:143], s[6:7], v0, s3, v[138:139]
	s_cmp_lg_u64 s[78:79], 0
	s_cselect_b64 s[6:7], -1, 0
	v_lshl_or_b32 v160, v0, 13, v138
	s_ff1_i32_b64 s80, s[78:79]
	v_mov_b32_e32 v143, v161
	s_and_b64 vcc, exec, s[6:7]
	v_mul_lo_u32 v152, v0, s22
	v_mul_lo_u32 v153, v0, s27
	s_cbranch_vccz .LBB0_255
	s_lshl_b64 s[8:9], s[80:81], 7
	s_mul_i32 s10, s80, 0x88c00
	s_add_u32 s10, s40, s10
	s_addc_u32 s11, s41, 0
	global_load_dwordx4 v[96:99], v142, s[10:11]
	s_add_u32 s8, s38, s8
	s_addc_u32 s9, s39, s9
	global_load_dwordx4 v[100:103], v160, s[8:9]
	v_mul_lo_u32 v1, v0, s22
	v_add3_u32 v1, s26, v1, v138
	s_waitcnt vmcnt(1)
	ds_write_b128 v1, v[96:99]
	v_mul_lo_u32 v1, v0, s27
	v_add3_u32 v1, s28, v1, v138
	s_waitcnt vmcnt(0)
	ds_write2_b64 v1, v[100:101], v[102:103] offset1:1
	s_cbranch_execnz .LBB0_240
